# attention softmax: deferred-max reference starts at 0 (shift-invariant; >8 rescale rule unchanged) and a wave-uniform fast path skips the 32 v_sub per key tile while the reference is 0; stacked on ear
# speedup vs baseline: 1.0028x; 1.0028x over previous
.LBB0_952:
	s_waitcnt vmcnt(4)
	ds_write_b128 v207, v[112:115]
	s_waitcnt vmcnt(3)
	ds_write_b128 v207, v[116:119] offset:128
	s_waitcnt vmcnt(2)
	ds_write_b128 v207, v[120:123] offset:256
	s_waitcnt vmcnt(1)
	ds_write_b128 v208, v[124:127] offset:25600
	s_waitcnt vmcnt(0)
	ds_write_b128 v208, v[128:131] offset:25664
	s_waitcnt lgkmcnt(0)
	s_cmp_lt_i32 s2, 1
	s_waitcnt lgkmcnt(0)
	s_barrier
	s_cbranch_scc1 .LBB0_964
	v_mov_b32_e32 v14, v0
	v_mov_b32_e32 v15, v0
	v_lshl_add_u64 v[196:197], v[2:3], 0, s[6:7]
	v_mov_b32_e32 v1, v0
	v_mov_b32_e32 v2, v0
	v_mov_b32_e32 v3, v0
	v_mov_b32_e32 v4, v0
	v_mov_b32_e32 v5, v0
	v_mov_b32_e32 v6, v0
	v_mov_b32_e32 v7, v0
	v_mov_b32_e32 v8, v0
	v_mov_b32_e32 v9, v0
	v_mov_b32_e32 v10, v0
	v_mov_b32_e32 v11, v0
	v_mov_b32_e32 v12, v0
	v_mov_b32_e32 v13, v0
	v_mov_b64_e32 v[30:31], v[14:15]
	v_mov_b64_e32 v[46:47], v[14:15]
	v_mov_b64_e32 v[62:63], v[14:15]
	v_mov_b64_e32 v[78:79], v[14:15]
	v_lshl_add_u64 v[198:199], s[30:31], 0, v[194:195]
	s_mov_b32 s35, 0
	v_mov_b32_e32 v214, 0
	v_mov_b32_e32 v213, 0
	v_mov_b64_e32 v[28:29], v[12:13]
	v_mov_b64_e32 v[26:27], v[10:11]
	v_mov_b64_e32 v[24:25], v[8:9]
	v_mov_b64_e32 v[22:23], v[6:7]
	v_mov_b64_e32 v[20:21], v[4:5]
	v_mov_b64_e32 v[18:19], v[2:3]
	v_mov_b64_e32 v[16:17], v[0:1]
	v_mov_b64_e32 v[44:45], v[12:13]
	v_mov_b64_e32 v[42:43], v[10:11]
	v_mov_b64_e32 v[40:41], v[8:9]
	v_mov_b64_e32 v[38:39], v[6:7]
	v_mov_b64_e32 v[36:37], v[4:5]
	v_mov_b64_e32 v[34:35], v[2:3]
	v_mov_b64_e32 v[32:33], v[0:1]
	v_mov_b64_e32 v[60:61], v[12:13]
	v_mov_b64_e32 v[58:59], v[10:11]
	v_mov_b64_e32 v[56:57], v[8:9]
	v_mov_b64_e32 v[54:55], v[6:7]
	v_mov_b64_e32 v[52:53], v[4:5]
	v_mov_b64_e32 v[50:51], v[2:3]
	v_mov_b64_e32 v[48:49], v[0:1]
	v_mov_b64_e32 v[76:77], v[12:13]
	v_mov_b64_e32 v[74:75], v[10:11]
	v_mov_b64_e32 v[72:73], v[8:9]
	v_mov_b64_e32 v[70:71], v[6:7]
	v_mov_b64_e32 v[68:69], v[4:5]
	v_mov_b64_e32 v[66:67], v[2:3]
	v_mov_b64_e32 v[64:65], v[0:1]

.LBB0_963:
	v_cmp_eq_f32_e32 vcc, 0, v214
	s_cmp_eq_u64 vcc, exec
	s_cbranch_scc1 .Lattn_fast
	v_sub_f32_e32 v15, v80, v214
	v_sub_f32_e32 v80, v97, v214
	v_exp_f32_e32 v216, v80
	v_sub_f32_e32 v80, v81, v214
	v_exp_f32_e32 v217, v80
	v_sub_f32_e32 v80, v98, v214
	v_exp_f32_e32 v218, v80
	v_sub_f32_e32 v80, v82, v214
	v_exp_f32_e32 v219, v80
	v_sub_f32_e32 v80, v99, v214
	v_exp_f32_e32 v220, v80
	v_sub_f32_e32 v80, v83, v214
	v_exp_f32_e32 v221, v80
	v_sub_f32_e32 v80, v100, v214
	v_exp_f32_e32 v222, v80
	v_sub_f32_e32 v80, v84, v214
	v_exp_f32_e32 v223, v80
	v_sub_f32_e32 v80, v101, v214
	v_exp_f32_e32 v224, v80
	v_sub_f32_e32 v80, v85, v214
	v_exp_f32_e32 v225, v80
	v_sub_f32_e32 v80, v102, v214
	v_exp_f32_e32 v226, v80
	v_sub_f32_e32 v80, v86, v214
	v_exp_f32_e32 v227, v80
	v_sub_f32_e32 v80, v103, v214
	v_exp_f32_e32 v228, v80
	v_sub_f32_e32 v80, v87, v214
	v_exp_f32_e32 v229, v80
	v_sub_f32_e32 v80, v104, v214
	v_exp_f32_e32 v230, v80
	v_sub_f32_e32 v80, v88, v214
	v_exp_f32_e32 v231, v80
	v_sub_f32_e32 v80, v105, v214
	v_exp_f32_e32 v232, v80
	v_sub_f32_e32 v80, v89, v214
	v_exp_f32_e32 v233, v80
	v_sub_f32_e32 v80, v106, v214
	v_exp_f32_e32 v234, v80
	v_sub_f32_e32 v80, v90, v214
	v_exp_f32_e32 v235, v80
	v_sub_f32_e32 v80, v107, v214
	v_exp_f32_e32 v236, v80
	v_sub_f32_e32 v80, v91, v214
	v_exp_f32_e32 v237, v80
	v_sub_f32_e32 v80, v108, v214
	v_exp_f32_e32 v238, v80
	v_sub_f32_e32 v80, v92, v214
	v_exp_f32_e32 v239, v80
	v_sub_f32_e32 v80, v109, v214
	v_exp_f32_e32 v240, v80
	v_sub_f32_e32 v80, v93, v214
	v_exp_f32_e32 v241, v80
	v_sub_f32_e32 v80, v110, v214
	v_exp_f32_e32 v242, v80
	v_sub_f32_e32 v80, v94, v214
	v_exp_f32_e32 v243, v80
	v_sub_f32_e32 v80, v111, v214
	v_sub_f32_e32 v14, v96, v214
	v_exp_f32_e32 v244, v80
	v_sub_f32_e32 v80, v95, v214
	v_exp_f32_e32 v14, v14
	v_exp_f32_e32 v15, v15
	v_exp_f32_e32 v245, v80
.Lattn_join:
	v_cvt_pk_bf16_f32 v96, v14, v216
	v_cvt_pk_bf16_f32 v104, v15, v217
	v_pk_add_f32 v[14:15], v[14:15], 0 op_sel_hi:[1,0]
	v_pk_add_f32 v[216:217], v[216:217], 0 op_sel_hi:[1,0]
	v_pk_add_f32 v[14:15], v[218:219], v[14:15]
	v_pk_add_f32 v[216:217], v[220:221], v[216:217]
	ds_read_b128 v[80:83], v1 offset:30208
	ds_read_b128 v[84:87], v1 offset:30240
	ds_read_b128 v[88:91], v1 offset:30272
	ds_read_b128 v[92:95], v1 offset:30304
	v_pk_add_f32 v[14:15], v[222:223], v[14:15]
	v_pk_add_f32 v[216:217], v[224:225], v[216:217]
	v_pk_add_f32 v[14:15], v[226:227], v[14:15]
	v_pk_add_f32 v[216:217], v[228:229], v[216:217]
	v_pk_add_f32 v[14:15], v[230:231], v[14:15]
	v_pk_add_f32 v[216:217], v[232:233], v[216:217]
	v_pk_add_f32 v[14:15], v[234:235], v[14:15]
	v_pk_add_f32 v[216:217], v[236:237], v[216:217]
	v_pk_add_f32 v[14:15], v[238:239], v[14:15]
	v_pk_add_f32 v[216:217], v[240:241], v[216:217]
	v_pk_add_f32 v[14:15], v[242:243], v[14:15]
	v_pk_add_f32 v[216:217], v[244:245], v[216:217]
	v_cvt_pk_bf16_f32 v97, v218, v220
	v_pk_add_f32 v[14:15], v[14:15], v[216:217]
	v_cvt_pk_bf16_f32 v98, v222, v224
	v_cvt_pk_bf16_f32 v99, v226, v228
	v_cvt_pk_bf16_f32 v100, v230, v232
	v_cvt_pk_bf16_f32 v101, v234, v236
	v_cvt_pk_bf16_f32 v102, v238, v240
	v_cvt_pk_bf16_f32 v103, v242, v244
	v_cvt_pk_bf16_f32 v105, v219, v221
	v_cvt_pk_bf16_f32 v106, v223, v225
	v_cvt_pk_bf16_f32 v107, v227, v229
	v_cvt_pk_bf16_f32 v108, v231, v233
	v_cvt_pk_bf16_f32 v109, v235, v237
	v_cvt_pk_bf16_f32 v110, v239, v241
	v_cvt_pk_bf16_f32 v111, v243, v245
	v_add_f32_e32 v14, v14, v15
	v_mfma_f32_32x32x16_bf16 v[64:79], v[180:183], v[96:99], v[64:79]
	v_mfma_f32_32x32x16_bf16 v[64:79], v[10:13], v[100:103], v[64:79]
	v_mfma_f32_32x32x16_bf16 v[64:79], v[6:9], v[104:107], v[64:79]
	v_mfma_f32_32x32x16_bf16 v[64:79], v[2:5], v[108:111], v[64:79]
	ds_read_b128 v[2:5], v1 offset:34816
	ds_read_b128 v[6:9], v1 offset:34848
	ds_read_b128 v[10:13], v1 offset:34880
	ds_read_b128 v[180:183], v1 offset:34912
	s_waitcnt lgkmcnt(7)
	v_mfma_f32_32x32x16_bf16 v[48:63], v[80:83], v[96:99], v[48:63]
	s_waitcnt lgkmcnt(6)
	v_mfma_f32_32x32x16_bf16 v[48:63], v[84:87], v[100:103], v[48:63]
	s_waitcnt lgkmcnt(5)
	v_mfma_f32_32x32x16_bf16 v[48:63], v[88:91], v[104:107], v[48:63]
	s_waitcnt lgkmcnt(4)
	v_mfma_f32_32x32x16_bf16 v[48:63], v[92:95], v[108:111], v[48:63]
	ds_read_b128 v[80:83], v1 offset:39424
	ds_read_b128 v[84:87], v1 offset:39456
	ds_read_b128 v[88:91], v1 offset:39488
	ds_read_b128 v[92:95], v1 offset:39520
	s_waitcnt lgkmcnt(7)
	v_mfma_f32_32x32x16_bf16 v[32:47], v[2:5], v[96:99], v[32:47]
	s_waitcnt lgkmcnt(6)
	v_mfma_f32_32x32x16_bf16 v[32:47], v[6:9], v[100:103], v[32:47]
	s_waitcnt lgkmcnt(5)
	v_mfma_f32_32x32x16_bf16 v[32:47], v[10:13], v[104:107], v[32:47]
	s_waitcnt lgkmcnt(4)
	v_mfma_f32_32x32x16_bf16 v[32:47], v[180:183], v[108:111], v[32:47]
	s_waitcnt lgkmcnt(3)
	v_mfma_f32_32x32x16_bf16 v[16:31], v[80:83], v[96:99], v[16:31]
	v_add_f32_e32 v213, v213, v14
	s_waitcnt lgkmcnt(2)
	v_mfma_f32_32x32x16_bf16 v[16:31], v[84:87], v[100:103], v[16:31]
	s_waitcnt lgkmcnt(1)
	v_mfma_f32_32x32x16_bf16 v[16:31], v[88:91], v[104:107], v[16:31]
	s_waitcnt lgkmcnt(0)
	v_mfma_f32_32x32x16_bf16 v[16:31], v[92:95], v[108:111], v[16:31]
	s_andn2_b64 vcc, exec, s[30:31]
	s_cbranch_vccz .LBB0_957
	s_branch .LBB0_958
.Lattn_fast:
	v_exp_f32_e32 v216, v97
	v_exp_f32_e32 v217, v81
	v_exp_f32_e32 v218, v98
	v_exp_f32_e32 v219, v82
	v_exp_f32_e32 v220, v99
	v_exp_f32_e32 v221, v83
	v_exp_f32_e32 v222, v100
	v_exp_f32_e32 v223, v84
	v_exp_f32_e32 v224, v101
	v_exp_f32_e32 v225, v85
	v_exp_f32_e32 v226, v102
	v_exp_f32_e32 v227, v86
	v_exp_f32_e32 v228, v103
	v_exp_f32_e32 v229, v87
	v_exp_f32_e32 v230, v104
	v_exp_f32_e32 v231, v88
	v_exp_f32_e32 v232, v105
	v_exp_f32_e32 v233, v89
	v_exp_f32_e32 v234, v106
	v_exp_f32_e32 v235, v90
	v_exp_f32_e32 v236, v107
	v_exp_f32_e32 v237, v91
	v_exp_f32_e32 v238, v108
	v_exp_f32_e32 v239, v92
	v_exp_f32_e32 v240, v109
	v_exp_f32_e32 v241, v93
	v_exp_f32_e32 v242, v110
	v_exp_f32_e32 v243, v94
	v_exp_f32_e32 v244, v111
	v_exp_f32_e32 v14, v96
	v_exp_f32_e32 v15, v80
	v_exp_f32_e32 v245, v95
	s_branch .Lattn_join
